# K-loop load segments: also the W_out phase's ds_read base registers hoisted (SGPR-base LDS-DMA in all four GEMM K-loops)
# speedup vs baseline: 1.0133x; 1.0013x over previous
; #define PG8_STAGE(bufoff, gbase, voff) do { _Pragma("unroll") for (int _i = 0; _i < 2; ++_i) \
;         __builtin_amdgcn_global_load_lds((const unsigned*)((const char*)(gbase) + (voff)[_i]), (PG8_LAS unsigned*)(lds + (bufoff) + ldsw + _i * 8192), 16, 0, 0); } while (0)
; #define PG8_LDA(dst, b, h) do { _Pragma("unroll") for (int m = 0; m < 4; ++m) _Pragma("unroll") for (int k = 0; k < 2; ++k) dst[m][k] = *(const PG8_LAS bf16x8*)(lds + PG8_SA(b, h) + aoff + m * 2048 + k * 1024); } while (0)
; #define PG8_LDB(dst, b, h) do { _Pragma("unroll") for (int n = 0; n < 2; ++n) _Pragma("unroll") for (int k = 0; k < 2; ++k) dst[n][k] = *(const PG8_LAS bf16x8*)(lds + PG8_SB(b, h) + boff + n * 2048 + k * 1024); } while (0)
; #define PG8_MMA(ai, bj, At, Bt) do { __builtin_amdgcn_s_setprio(1); _Pragma("unroll") for (int m = 0; m < 4; ++m) _Pragma("unroll") for (int n = 0; n < 2; ++n) _Pragma("unroll") for (int k = 0; k < 2; ++k) \
;         acc[ai][bj][m][n] = __builtin_amdgcn_mfma_f32_16x16x32_bf16(Bt[n][k], At[m][k], acc[ai][bj][m][n], 0, 0, 0); __builtin_amdgcn_s_setprio(0); } while (0)
; #define PG8_WAIT_V(n) asm volatile("s_waitcnt vmcnt(" #n ")" ::: "memory")
; #define PG8_WAIT_L(n) asm volatile("s_waitcnt lgkmcnt(" #n ")" ::: "memory")
; #define PG8_BAR __builtin_amdgcn_s_barrier()
; #define PG8_SCHED __builtin_amdgcn_sched_barrier(0)
; template <class Epi, class Sched, bool ALIGN_EPI = false, bool SP2 = false>
; __device__ __forceinline__ void gemm_phase(PG8_LAS unsigned char* lds, const Gemm g, const Sched& S, const Epi& E) {
;     ...
;             PG8_LDB(B0, 0, 0); PG8_LDB(B1, 0, 1); PG8_SCHED; PG8_LDA(At, 0, 0); PG8_STAGE(PG8_SA(1, 1), a1 + hstep, voffA);
;             PG8_WAIT_V(8); PG8_WAIT_L(0); PG8_BAR; PG8_MMA(0, 0, At, B0); PG8_MMA(0, 1, At, B1); PG8_BAR; PG8_SCHED;
;     ...
; #pragma unroll
;         for (int a = 0; a < 2; ++a)
; #pragma unroll
;             for (int b = 0; b < 2; ++b)
; #pragma unroll
;                 for (int m = 0; m < 4; ++m)
; #pragma unroll
;                     for (int n = 0; n < 2; ++n) acc[a][b][m][n] = (f32x4){0.f, 0.f, 0.f, 0.f};
;         cur = nxt; cA = nA; cB = nB; ++ui;
.LBB0_925:
	s_add_i32 s59, s59, 1
	s_mov_b64 s[2:3], s[10:11]
	s_lshl_b32 s10, s59, 3
	v_readlane_b32 s16, v248, 25
	s_mov_b32 s60, s42
	s_add_i32 s42, s10, s16
	s_cmp_lt_i32 s42, 8
	s_cselect_b64 s[44:45], -1, 0
	s_ashr_i32 s43, s42, 31
	s_lshl_b64 s[10:11], s[42:43], 20
	s_add_u32 s10, s52, s10
	s_addc_u32 s11, s53, s11
	v_mov_b32_e32 v3, v2
	s_and_b64 s[46:47], s[44:45], exec
	v_mov_b32_e32 v0, v2
	s_waitcnt lgkmcnt(0)
	v_mov_b32_e32 v1, v2
	v_mov_b64_e32 v[6:7], v[2:3]
	v_mov_b64_e32 v[10:11], v[2:3]
	v_mov_b64_e32 v[22:23], v[2:3]
	v_mov_b64_e32 v[26:27], v[2:3]
	v_mov_b64_e32 v[38:39], v[2:3]
	v_mov_b64_e32 v[42:43], v[2:3]
	v_mov_b64_e32 v[54:55], v[2:3]
	v_mov_b64_e32 v[58:59], v[2:3]
	v_mov_b64_e32 v[14:15], v[2:3]
	v_mov_b64_e32 v[18:19], v[2:3]
	v_mov_b64_e32 v[30:31], v[2:3]
	v_mov_b64_e32 v[34:35], v[2:3]
	v_mov_b64_e32 v[46:47], v[2:3]
	v_mov_b64_e32 v[50:51], v[2:3]
	v_mov_b64_e32 v[62:63], v[2:3]
	v_mov_b64_e32 v[66:67], v[2:3]
	v_mov_b64_e32 v[70:71], v[2:3]
	v_mov_b64_e32 v[74:75], v[2:3]
	v_mov_b64_e32 v[86:87], v[2:3]
	v_mov_b64_e32 v[90:91], v[2:3]
	v_mov_b64_e32 v[102:103], v[2:3]
	v_mov_b64_e32 v[106:107], v[2:3]
	v_mov_b64_e32 v[118:119], v[2:3]
	v_mov_b64_e32 v[122:123], v[2:3]
	v_mov_b64_e32 v[78:79], v[2:3]
	v_mov_b64_e32 v[82:83], v[2:3]
	v_mov_b64_e32 v[94:95], v[2:3]
	v_mov_b64_e32 v[98:99], v[2:3]
	v_mov_b64_e32 v[110:111], v[2:3]
	v_mov_b64_e32 v[114:115], v[2:3]
	v_mov_b64_e32 v[126:127], v[2:3]
	v_mov_b64_e32 v[130:131], v[2:3]
	s_cselect_b32 s43, s11, s3
	s_cselect_b32 s61, s10, s2
	s_mov_b32 s66, -2
	s_mov_b64 s[46:47], 0
	v_mov_b64_e32 v[4:5], v[0:1]
	v_mov_b64_e32 v[8:9], v[0:1]
	v_mov_b64_e32 v[20:21], v[0:1]
	v_mov_b64_e32 v[24:25], v[0:1]
	v_mov_b64_e32 v[36:37], v[0:1]
	v_mov_b64_e32 v[40:41], v[0:1]
	v_mov_b64_e32 v[52:53], v[0:1]
	v_mov_b64_e32 v[56:57], v[0:1]
	v_mov_b64_e32 v[12:13], v[0:1]
	v_mov_b64_e32 v[16:17], v[0:1]
	v_mov_b64_e32 v[28:29], v[0:1]
	v_mov_b64_e32 v[32:33], v[0:1]
	v_mov_b64_e32 v[44:45], v[0:1]
	v_mov_b64_e32 v[48:49], v[0:1]
	v_mov_b64_e32 v[60:61], v[0:1]
	v_mov_b64_e32 v[64:65], v[0:1]
	v_mov_b64_e32 v[68:69], v[0:1]
	v_mov_b64_e32 v[72:73], v[0:1]
	v_mov_b64_e32 v[84:85], v[0:1]
	v_mov_b64_e32 v[88:89], v[0:1]
	v_mov_b64_e32 v[100:101], v[0:1]
	v_mov_b64_e32 v[104:105], v[0:1]
	v_mov_b64_e32 v[116:117], v[0:1]
	v_mov_b64_e32 v[120:121], v[0:1]
	v_mov_b64_e32 v[76:77], v[0:1]
	v_mov_b64_e32 v[80:81], v[0:1]
	v_mov_b64_e32 v[92:93], v[0:1]
	v_mov_b64_e32 v[96:97], v[0:1]
	v_mov_b64_e32 v[108:109], v[0:1]
	v_mov_b64_e32 v[112:113], v[0:1]
	v_mov_b64_e32 v[124:125], v[0:1]
	v_mov_b64_e32 v[128:129], v[0:1]
	v_readlane_b32 s17, v248, 26
	s_branch .LBB0_927
	v_add_u32_e32 v168, 0x10000, v192
	v_add_u32_e32 v169, 0x14000, v192
	v_add_u32_e32 v170, 0x18000, v192
	v_add_u32_e32 v171, 0x1c000, v192
.LBB0_926:
	s_add_u32 s2, s31, s46
	s_addc_u32 s3, s91, s47
	s_add_u32 s2, s2, 0x1ba00100
	s_addc_u32 s3, s3, 0
	s_add_u32 s67, s36, s46
	s_addc_u32 s68, s37, s47
	s_cmpk_eq_i32 s46, 0xf00
	s_cselect_b32 s49, s89, s3
	s_cselect_b32 s48, s88, s2
	s_cselect_b32 s3, s43, s68
	s_cselect_b32 s2, s61, s67
	s_add_i32 s67, 0, 0x10000
	s_add_i32 s70, 0, 0x14000
	ds_read_b128 v[132:135], v168
	ds_read_b128 v[136:139], v168 offset:1024
	ds_read_b128 v[140:143], v168 offset:2048
	ds_read_b128 v[144:147], v168 offset:3072
	ds_read_b128 v[148:151], v169
	ds_read_b128 v[152:155], v169 offset:1024
	ds_read_b128 v[180:183], v169 offset:2048
	ds_read_b128 v[184:187], v169 offset:3072
	v_lshl_add_u64 v[0:1], v[176:177], 0, s[46:47]
	s_add_i32 m0, s51, 0xc000
	ds_read_b128 v[188:191], v195
	ds_read_b128 v[196:199], v195 offset:1024
	ds_read_b128 v[200:203], v195 offset:2048
	ds_read_b128 v[212:215], v195 offset:3072
	ds_read_b128 v[216:219], v195 offset:4096
	ds_read_b128 v[220:223], v195 offset:5120
	ds_read_b128 v[224:227], v195 offset:6144
	ds_read_b128 v[228:231], v195 offset:7168
	global_load_lds_dwordx4 v[0:1], off
	v_lshl_add_u64 v[0:1], v[178:179], 0, s[46:47]
	s_add_i32 m0, s51, 0xe000
	s_nop 0
	global_load_lds_dwordx4 v[0:1], off
	s_waitcnt vmcnt(8)
	s_waitcnt lgkmcnt(0)
	s_barrier
	s_setprio 1
	s_waitcnt lgkmcnt(0)
	v_mfma_f32_16x16x32_bf16 v[128:131], v[132:135], v[188:191], v[128:131]
	v_mfma_f32_16x16x32_bf16 v[124:127], v[140:143], v[188:191], v[124:127]
	v_mfma_f32_16x16x32_bf16 v[112:115], v[132:135], v[200:203], v[112:115]
	v_mfma_f32_16x16x32_bf16 v[108:111], v[140:143], v[200:203], v[108:111]
	v_mfma_f32_16x16x32_bf16 v[96:99], v[132:135], v[216:219], v[96:99]
	v_mfma_f32_16x16x32_bf16 v[92:95], v[140:143], v[216:219], v[92:95]
	v_mfma_f32_16x16x32_bf16 v[80:83], v[132:135], v[224:227], v[80:83]
	v_mfma_f32_16x16x32_bf16 v[76:79], v[140:143], v[224:227], v[76:79]
	v_mfma_f32_16x16x32_bf16 v[128:131], v[136:139], v[196:199], v[128:131]
	v_mfma_f32_16x16x32_bf16 v[124:127], v[144:147], v[196:199], v[124:127]
	v_mfma_f32_16x16x32_bf16 v[112:115], v[136:139], v[212:215], v[112:115]
	v_mfma_f32_16x16x32_bf16 v[108:111], v[144:147], v[212:215], v[108:111]
	v_mfma_f32_16x16x32_bf16 v[96:99], v[136:139], v[220:223], v[96:99]
	v_mfma_f32_16x16x32_bf16 v[92:95], v[144:147], v[220:223], v[92:95]
	v_mfma_f32_16x16x32_bf16 v[80:83], v[136:139], v[228:231], v[80:83]
	v_mfma_f32_16x16x32_bf16 v[76:79], v[144:147], v[228:231], v[76:79]
	s_setprio 0
	s_setprio 1
	v_mfma_f32_16x16x32_bf16 v[120:123], v[148:151], v[188:191], v[120:123]
	v_mfma_f32_16x16x32_bf16 v[116:119], v[180:183], v[188:191], v[116:119]
	v_mfma_f32_16x16x32_bf16 v[104:107], v[148:151], v[200:203], v[104:107]
	v_mfma_f32_16x16x32_bf16 v[100:103], v[180:183], v[200:203], v[100:103]
	v_mfma_f32_16x16x32_bf16 v[88:91], v[148:151], v[216:219], v[88:91]
	v_mfma_f32_16x16x32_bf16 v[84:87], v[180:183], v[216:219], v[84:87]
	v_mfma_f32_16x16x32_bf16 v[72:75], v[148:151], v[224:227], v[72:75]
	v_mfma_f32_16x16x32_bf16 v[68:71], v[180:183], v[224:227], v[68:71]
	v_mfma_f32_16x16x32_bf16 v[120:123], v[152:155], v[196:199], v[120:123]
	v_mfma_f32_16x16x32_bf16 v[116:119], v[184:187], v[196:199], v[116:119]
	v_mfma_f32_16x16x32_bf16 v[104:107], v[152:155], v[212:215], v[104:107]
	v_mfma_f32_16x16x32_bf16 v[100:103], v[184:187], v[212:215], v[100:103]
	v_mfma_f32_16x16x32_bf16 v[88:91], v[152:155], v[220:223], v[88:91]
	v_mfma_f32_16x16x32_bf16 v[84:87], v[184:187], v[220:223], v[84:87]
	v_mfma_f32_16x16x32_bf16 v[72:75], v[152:155], v[228:231], v[72:75]
	v_mfma_f32_16x16x32_bf16 v[68:71], v[184:187], v[228:231], v[68:71]
	s_setprio 0
	s_barrier
; #define PG8_STAGE(bufoff, gbase, voff) do { _Pragma("unroll") for (int _i = 0; _i < 2; ++_i) \
;         __builtin_amdgcn_global_load_lds((const unsigned*)((const char*)(gbase) + (voff)[_i]), (PG8_LAS unsigned*)(lds + (bufoff) + ldsw + _i * 8192), 16, 0, 0); } while (0)
; #define PG8_LDA(dst, b, h) do { _Pragma("unroll") for (int m = 0; m < 4; ++m) _Pragma("unroll") for (int k = 0; k < 2; ++k) dst[m][k] = *(const PG8_LAS bf16x8*)(lds + PG8_SA(b, h) + aoff + m * 2048 + k * 1024); } while (0)
; #define PG8_LDB(dst, b, h) do { _Pragma("unroll") for (int n = 0; n < 2; ++n) _Pragma("unroll") for (int k = 0; k < 2; ++k) dst[n][k] = *(const PG8_LAS bf16x8*)(lds + PG8_SB(b, h) + boff + n * 2048 + k * 1024); } while (0)
; #define PG8_MMA(ai, bj, At, Bt) do { __builtin_amdgcn_s_setprio(1); _Pragma("unroll") for (int m = 0; m < 4; ++m) _Pragma("unroll") for (int n = 0; n < 2; ++n) _Pragma("unroll") for (int k = 0; k < 2; ++k) \
;         acc[ai][bj][m][n] = __builtin_amdgcn_mfma_f32_16x16x32_bf16(Bt[n][k], At[m][k], acc[ai][bj][m][n], 0, 0, 0); __builtin_amdgcn_s_setprio(0); } while (0)
; #define PG8_WAIT_V(n) asm volatile("s_waitcnt vmcnt(" #n ")" ::: "memory")
; #define PG8_WAIT_L(n) asm volatile("s_waitcnt lgkmcnt(" #n ")" ::: "memory")
; #define PG8_BAR __builtin_amdgcn_s_barrier()
; #define PG8_SCHED __builtin_amdgcn_sched_barrier(0)
; template <class Epi, class Sched, bool ALIGN_EPI = false, bool SP2 = false>
; __device__ __forceinline__ void gemm_phase(PG8_LAS unsigned char* lds, const Gemm g, const Sched& S, const Epi& E) {
;     ...
;             PG8_WAIT_V(8); PG8_WAIT_L(0); PG8_BAR; PG8_MMA(1, 0, At, B0); PG8_MMA(1, 1, At, B1); PG8_BAR; PG8_SCHED;
;             PG8_LDB(B0, 1, 0); PG8_LDB(B1, 1, 1); PG8_SCHED; PG8_LDA(At, 1, 0); PG8_STAGE(PG8_SA(0, 1), a2 + hstep, voffA);
;             PG8_WAIT_V(8); PG8_WAIT_L(0); PG8_BAR; PG8_MMA(0, 0, At, B0); PG8_MMA(0, 1, At, B1); PG8_BAR; PG8_SCHED;
;             PG8_LDA(At, 1, 1); PG8_STAGE(PG8_SB(1, 0), b3, voffB); PG8_STAGE(PG8_SB(1, 1), b3 + hstep, voffB); PG8_STAGE(PG8_SA(1, 0), a3, voffA);
	s_add_i32 s67, s67, s50
	s_add_u32 s98, s2, 0x80
	s_addc_u32 s99, s3, 0
	s_mov_b32 m0, s67
	ds_read_b128 v[188:191], v195 offset:16384
	ds_read_b128 v[196:199], v195 offset:17408
	ds_read_b128 v[200:203], v195 offset:18432
	ds_read_b128 v[212:215], v195 offset:19456
	ds_read_b128 v[216:219], v195 offset:20480
	ds_read_b128 v[220:223], v195 offset:21504
	ds_read_b128 v[224:227], v195 offset:22528
	ds_read_b128 v[228:231], v195 offset:23552
	global_load_lds_dwordx4 v172, s[2:3]
	s_add_i32 m0, s67, 0x2000
	s_add_u32 s68, s2, 0x80000
	s_addc_u32 s69, s3, 0
	s_add_i32 s67, s70, s50
	global_load_lds_dwordx4 v156, s[2:3]
	s_mov_b32 m0, s67
	s_add_u32 s100, s48, 0x80
	s_addc_u32 s101, s49, 0
	s_nop 0
	global_load_lds_dwordx4 v172, s[68:69]
	s_add_i32 m0, s67, 0x2000
	s_nop 0
	global_load_lds_dwordx4 v156, s[68:69]
	s_mov_b32 m0, s51
	s_nop 0
	global_load_lds_dwordx4 v174, s[48:49]
	s_mov_b32 m0, s54
	s_nop 0
	global_load_lds_dwordx4 v158, s[48:49]
	s_waitcnt vmcnt(8)
	s_waitcnt lgkmcnt(0)
	s_barrier
	s_setprio 1
	s_waitcnt lgkmcnt(0)
	v_mfma_f32_16x16x32_bf16 v[64:67], v[132:135], v[188:191], v[64:67]
	v_mfma_f32_16x16x32_bf16 v[60:63], v[140:143], v[188:191], v[60:63]
	v_mfma_f32_16x16x32_bf16 v[48:51], v[132:135], v[200:203], v[48:51]
	v_mfma_f32_16x16x32_bf16 v[44:47], v[140:143], v[200:203], v[44:47]
	v_mfma_f32_16x16x32_bf16 v[32:35], v[132:135], v[216:219], v[32:35]
	v_mfma_f32_16x16x32_bf16 v[28:31], v[140:143], v[216:219], v[28:31]
	v_mfma_f32_16x16x32_bf16 v[16:19], v[132:135], v[224:227], v[16:19]
	v_mfma_f32_16x16x32_bf16 v[12:15], v[140:143], v[224:227], v[12:15]
	v_mfma_f32_16x16x32_bf16 v[64:67], v[136:139], v[196:199], v[64:67]
	v_mfma_f32_16x16x32_bf16 v[60:63], v[144:147], v[196:199], v[60:63]
	v_mfma_f32_16x16x32_bf16 v[48:51], v[136:139], v[212:215], v[48:51]
	v_mfma_f32_16x16x32_bf16 v[44:47], v[144:147], v[212:215], v[44:47]
	v_mfma_f32_16x16x32_bf16 v[32:35], v[136:139], v[220:223], v[32:35]
	v_mfma_f32_16x16x32_bf16 v[28:31], v[144:147], v[220:223], v[28:31]
	v_mfma_f32_16x16x32_bf16 v[16:19], v[136:139], v[228:231], v[16:19]
	v_mfma_f32_16x16x32_bf16 v[12:15], v[144:147], v[228:231], v[12:15]
	s_setprio 0
	s_setprio 1
	v_mfma_f32_16x16x32_bf16 v[56:59], v[148:151], v[188:191], v[56:59]
	v_mfma_f32_16x16x32_bf16 v[52:55], v[180:183], v[188:191], v[52:55]
	v_mfma_f32_16x16x32_bf16 v[40:43], v[148:151], v[200:203], v[40:43]
	v_mfma_f32_16x16x32_bf16 v[36:39], v[180:183], v[200:203], v[36:39]
	v_mfma_f32_16x16x32_bf16 v[24:27], v[148:151], v[216:219], v[24:27]
	v_mfma_f32_16x16x32_bf16 v[20:23], v[180:183], v[216:219], v[20:23]
	v_mfma_f32_16x16x32_bf16 v[8:11], v[148:151], v[224:227], v[8:11]
	v_mfma_f32_16x16x32_bf16 v[4:7], v[180:183], v[224:227], v[4:7]
	v_mfma_f32_16x16x32_bf16 v[56:59], v[152:155], v[196:199], v[56:59]
	v_mfma_f32_16x16x32_bf16 v[52:55], v[184:187], v[196:199], v[52:55]
	v_mfma_f32_16x16x32_bf16 v[40:43], v[152:155], v[212:215], v[40:43]
	v_mfma_f32_16x16x32_bf16 v[36:39], v[184:187], v[212:215], v[36:39]
	v_mfma_f32_16x16x32_bf16 v[24:27], v[152:155], v[220:223], v[24:27]
	v_mfma_f32_16x16x32_bf16 v[20:23], v[184:187], v[220:223], v[20:23]
	v_mfma_f32_16x16x32_bf16 v[8:11], v[152:155], v[228:231], v[8:11]
	v_mfma_f32_16x16x32_bf16 v[4:7], v[184:187], v[228:231], v[4:7]
	s_setprio 0
	s_barrier
	s_add_i32 s67, 0, 0x18000
	s_add_i32 s68, 0, 0x1c000
	ds_read_b128 v[132:135], v170
	ds_read_b128 v[136:139], v170 offset:1024
	ds_read_b128 v[140:143], v170 offset:2048
	ds_read_b128 v[144:147], v170 offset:3072
	ds_read_b128 v[148:151], v171
	ds_read_b128 v[152:155], v171 offset:1024
	ds_read_b128 v[180:183], v171 offset:2048
	ds_read_b128 v[184:187], v171 offset:3072
	s_add_u32 s48, s48, 0x80000
	s_addc_u32 s49, s49, 0
	s_mov_b32 m0, s55
	ds_read_b128 v[188:191], v195 offset:32768
	ds_read_b128 v[196:199], v195 offset:33792
	ds_read_b128 v[200:203], v195 offset:34816
	ds_read_b128 v[212:215], v195 offset:35840
	ds_read_b128 v[216:219], v195 offset:36864
	ds_read_b128 v[220:223], v195 offset:37888
	ds_read_b128 v[224:227], v195 offset:38912
	ds_read_b128 v[228:231], v195 offset:39936
	global_load_lds_dwordx4 v174, s[48:49]
	s_mov_b32 m0, s56
	s_nop 0
	global_load_lds_dwordx4 v158, s[48:49]
	s_waitcnt vmcnt(8)
	s_waitcnt lgkmcnt(0)
	s_barrier
; #define PG8_STAGE(bufoff, gbase, voff) do { _Pragma("unroll") for (int _i = 0; _i < 2; ++_i) \
;         __builtin_amdgcn_global_load_lds((const unsigned*)((const char*)(gbase) + (voff)[_i]), (PG8_LAS unsigned*)(lds + (bufoff) + ldsw + _i * 8192), 16, 0, 0); } while (0)
; #define PG8_LDA(dst, b, h) do { _Pragma("unroll") for (int m = 0; m < 4; ++m) _Pragma("unroll") for (int k = 0; k < 2; ++k) dst[m][k] = *(const PG8_LAS bf16x8*)(lds + PG8_SA(b, h) + aoff + m * 2048 + k * 1024); } while (0)
; #define PG8_LDB(dst, b, h) do { _Pragma("unroll") for (int n = 0; n < 2; ++n) _Pragma("unroll") for (int k = 0; k < 2; ++k) dst[n][k] = *(const PG8_LAS bf16x8*)(lds + PG8_SB(b, h) + boff + n * 2048 + k * 1024); } while (0)
; #define PG8_MMA(ai, bj, At, Bt) do { __builtin_amdgcn_s_setprio(1); _Pragma("unroll") for (int m = 0; m < 4; ++m) _Pragma("unroll") for (int n = 0; n < 2; ++n) _Pragma("unroll") for (int k = 0; k < 2; ++k) \
;         acc[ai][bj][m][n] = __builtin_amdgcn_mfma_f32_16x16x32_bf16(Bt[n][k], At[m][k], acc[ai][bj][m][n], 0, 0, 0); __builtin_amdgcn_s_setprio(0); } while (0)
; #define PG8_WAIT_V(n) asm volatile("s_waitcnt vmcnt(" #n ")" ::: "memory")
; #define PG8_WAIT_L(n) asm volatile("s_waitcnt lgkmcnt(" #n ")" ::: "memory")
; #define PG8_BAR __builtin_amdgcn_s_barrier()
; #define PG8_SCHED __builtin_amdgcn_sched_barrier(0)
; template <class Epi, class Sched, bool ALIGN_EPI = false, bool SP2 = false>
; __device__ __forceinline__ void gemm_phase(PG8_LAS unsigned char* lds, const Gemm g, const Sched& S, const Epi& E) {
;     ...
;             PG8_WAIT_V(8); PG8_WAIT_L(0); PG8_BAR; PG8_MMA(1, 0, At, B0); PG8_MMA(1, 1, At, B1); PG8_BAR; PG8_SCHED;
;             PG8_LDB(B0, 1, 0); PG8_LDB(B1, 1, 1); PG8_SCHED; PG8_LDA(At, 1, 0); PG8_STAGE(PG8_SA(0, 1), a2 + hstep, voffA);
;             PG8_WAIT_V(8); PG8_WAIT_L(0); PG8_BAR; PG8_MMA(0, 0, At, B0); PG8_MMA(0, 1, At, B1); PG8_BAR; PG8_SCHED;
;             PG8_LDA(At, 1, 1); PG8_STAGE(PG8_SB(1, 0), b3, voffB); PG8_STAGE(PG8_SB(1, 1), b3 + hstep, voffB); PG8_STAGE(PG8_SA(1, 0), a3, voffA);
;             PG8_WAIT_V(8); PG8_WAIT_L(0); PG8_BAR; PG8_MMA(1, 0, At, B0); PG8_MMA(1, 1, At, B1); PG8_BAR; PG8_SCHED;
	s_setprio 1
	s_waitcnt lgkmcnt(0)
	v_mfma_f32_16x16x32_bf16 v[128:131], v[132:135], v[188:191], v[128:131]
	v_mfma_f32_16x16x32_bf16 v[124:127], v[140:143], v[188:191], v[124:127]
	v_mfma_f32_16x16x32_bf16 v[112:115], v[132:135], v[200:203], v[112:115]
	v_mfma_f32_16x16x32_bf16 v[108:111], v[140:143], v[200:203], v[108:111]
	v_mfma_f32_16x16x32_bf16 v[96:99], v[132:135], v[216:219], v[96:99]
	v_mfma_f32_16x16x32_bf16 v[92:95], v[140:143], v[216:219], v[92:95]
	v_mfma_f32_16x16x32_bf16 v[80:83], v[132:135], v[224:227], v[80:83]
	v_mfma_f32_16x16x32_bf16 v[76:79], v[140:143], v[224:227], v[76:79]
	v_mfma_f32_16x16x32_bf16 v[128:131], v[136:139], v[196:199], v[128:131]
	v_mfma_f32_16x16x32_bf16 v[124:127], v[144:147], v[196:199], v[124:127]
	v_mfma_f32_16x16x32_bf16 v[112:115], v[136:139], v[212:215], v[112:115]
	v_mfma_f32_16x16x32_bf16 v[108:111], v[144:147], v[212:215], v[108:111]
	v_mfma_f32_16x16x32_bf16 v[96:99], v[136:139], v[220:223], v[96:99]
	v_mfma_f32_16x16x32_bf16 v[92:95], v[144:147], v[220:223], v[92:95]
	v_mfma_f32_16x16x32_bf16 v[80:83], v[136:139], v[228:231], v[80:83]
	v_mfma_f32_16x16x32_bf16 v[76:79], v[144:147], v[228:231], v[76:79]
	s_setprio 0
	s_setprio 1
	v_mfma_f32_16x16x32_bf16 v[120:123], v[148:151], v[188:191], v[120:123]
	v_mfma_f32_16x16x32_bf16 v[116:119], v[180:183], v[188:191], v[116:119]
	v_mfma_f32_16x16x32_bf16 v[104:107], v[148:151], v[200:203], v[104:107]
	v_mfma_f32_16x16x32_bf16 v[100:103], v[180:183], v[200:203], v[100:103]
	v_mfma_f32_16x16x32_bf16 v[88:91], v[148:151], v[216:219], v[88:91]
	v_mfma_f32_16x16x32_bf16 v[84:87], v[180:183], v[216:219], v[84:87]
	v_mfma_f32_16x16x32_bf16 v[72:75], v[148:151], v[224:227], v[72:75]
	v_mfma_f32_16x16x32_bf16 v[68:71], v[180:183], v[224:227], v[68:71]
	v_mfma_f32_16x16x32_bf16 v[120:123], v[152:155], v[196:199], v[120:123]
	v_mfma_f32_16x16x32_bf16 v[116:119], v[184:187], v[196:199], v[116:119]
	v_mfma_f32_16x16x32_bf16 v[104:107], v[152:155], v[212:215], v[104:107]
	v_mfma_f32_16x16x32_bf16 v[100:103], v[184:187], v[212:215], v[100:103]
	v_mfma_f32_16x16x32_bf16 v[88:91], v[152:155], v[220:223], v[88:91]
	v_mfma_f32_16x16x32_bf16 v[84:87], v[184:187], v[220:223], v[84:87]
	v_mfma_f32_16x16x32_bf16 v[72:75], v[152:155], v[228:231], v[72:75]
	v_mfma_f32_16x16x32_bf16 v[68:71], v[184:187], v[228:231], v[68:71]
	s_setprio 0
	s_barrier
	s_add_i32 s48, s67, s50
	s_mov_b32 m0, s48
	ds_read_b128 v[188:191], v195 offset:49152
	ds_read_b128 v[196:199], v195 offset:50176
	ds_read_b128 v[200:203], v195 offset:51200
	ds_read_b128 v[212:215], v195 offset:52224
	ds_read_b128 v[216:219], v195 offset:53248
	ds_read_b128 v[220:223], v195 offset:54272
	ds_read_b128 v[224:227], v195 offset:55296
	ds_read_b128 v[228:231], v195 offset:56320
	global_load_lds_dwordx4 v172, s[98:99]
	s_add_i32 m0, s48, 0x2000
	s_add_u32 s2, s2, 0x80080
	s_addc_u32 s3, s3, 0
	s_add_i32 s48, s68, s50
	global_load_lds_dwordx4 v156, s[98:99]
	s_mov_b32 m0, s48
	s_nop 0
	global_load_lds_dwordx4 v172, s[2:3]
	s_add_i32 m0, s48, 0x2000
	s_nop 0
	global_load_lds_dwordx4 v156, s[2:3]
	s_mov_b32 m0, s57
	s_nop 0
	global_load_lds_dwordx4 v174, s[100:101]
	s_mov_b32 m0, s58
	s_nop 0
	global_load_lds_dwordx4 v158, s[100:101]
	s_waitcnt vmcnt(8)
	s_waitcnt lgkmcnt(0)
	s_barrier
	s_setprio 1
	s_waitcnt lgkmcnt(0)
	v_mfma_f32_16x16x32_bf16 v[64:67], v[132:135], v[188:191], v[64:67]
	v_mfma_f32_16x16x32_bf16 v[60:63], v[140:143], v[188:191], v[60:63]
	v_mfma_f32_16x16x32_bf16 v[48:51], v[132:135], v[200:203], v[48:51]
	v_mfma_f32_16x16x32_bf16 v[44:47], v[140:143], v[200:203], v[44:47]
	v_mfma_f32_16x16x32_bf16 v[32:35], v[132:135], v[216:219], v[32:35]
	v_mfma_f32_16x16x32_bf16 v[28:31], v[140:143], v[216:219], v[28:31]
	v_mfma_f32_16x16x32_bf16 v[16:19], v[132:135], v[224:227], v[16:19]
	v_mfma_f32_16x16x32_bf16 v[12:15], v[140:143], v[224:227], v[12:15]
	v_mfma_f32_16x16x32_bf16 v[64:67], v[136:139], v[196:199], v[64:67]
	v_mfma_f32_16x16x32_bf16 v[60:63], v[144:147], v[196:199], v[60:63]
	v_mfma_f32_16x16x32_bf16 v[48:51], v[136:139], v[212:215], v[48:51]
	v_mfma_f32_16x16x32_bf16 v[44:47], v[144:147], v[212:215], v[44:47]
	v_mfma_f32_16x16x32_bf16 v[32:35], v[136:139], v[220:223], v[32:35]
	v_mfma_f32_16x16x32_bf16 v[28:31], v[144:147], v[220:223], v[28:31]
	v_mfma_f32_16x16x32_bf16 v[16:19], v[136:139], v[228:231], v[16:19]
	v_mfma_f32_16x16x32_bf16 v[12:15], v[144:147], v[228:231], v[12:15]
	s_setprio 0
	s_setprio 1
	v_mfma_f32_16x16x32_bf16 v[56:59], v[148:151], v[188:191], v[56:59]
	v_mfma_f32_16x16x32_bf16 v[52:55], v[180:183], v[188:191], v[52:55]
	v_mfma_f32_16x16x32_bf16 v[40:43], v[148:151], v[200:203], v[40:43]
	v_mfma_f32_16x16x32_bf16 v[36:39], v[180:183], v[200:203], v[36:39]
	v_mfma_f32_16x16x32_bf16 v[24:27], v[148:151], v[216:219], v[24:27]
	v_mfma_f32_16x16x32_bf16 v[20:23], v[180:183], v[216:219], v[20:23]
	v_mfma_f32_16x16x32_bf16 v[8:11], v[148:151], v[224:227], v[8:11]
	v_mfma_f32_16x16x32_bf16 v[4:7], v[180:183], v[224:227], v[4:7]
	v_mfma_f32_16x16x32_bf16 v[56:59], v[152:155], v[196:199], v[56:59]
	v_mfma_f32_16x16x32_bf16 v[52:55], v[184:187], v[196:199], v[52:55]
	v_mfma_f32_16x16x32_bf16 v[40:43], v[152:155], v[212:215], v[40:43]
	v_mfma_f32_16x16x32_bf16 v[36:39], v[184:187], v[212:215], v[36:39]
	v_mfma_f32_16x16x32_bf16 v[24:27], v[152:155], v[220:223], v[24:27]
	v_mfma_f32_16x16x32_bf16 v[20:23], v[184:187], v[220:223], v[20:23]
	v_mfma_f32_16x16x32_bf16 v[8:11], v[152:155], v[228:231], v[8:11]
	v_mfma_f32_16x16x32_bf16 v[4:7], v[184:187], v[228:231], v[4:7]
	s_setprio 0
	s_barrier
	s_add_i32 s66, s66, 2
	s_add_u32 s46, s46, 0x100
	s_addc_u32 s47, s47, 0
	s_cmp_gt_u32 s66, 29
	s_cbranch_scc1 .LBB0_929
